# MLA interior loop: next-iteration DMA addresses and write-buffer base computed before the loop-back barrier; after the barrier the first K-fragment ds_reads are issued before the LDS-DMA loads (back-e
# speedup vs baseline: 1.0060x; 1.0060x over previous
.LBB0_347:
	s_lshl_b64 s[0:1], s[50:51], 1
	s_mov_b64 s[2:3], s[10:11]
	s_add_u32 s10, s2, s0
	s_addc_u32 s11, s3, s1
	v_readlane_b32 s4, v255, 34
	v_readlane_b32 s5, v255, 35
	s_add_u32 s12, s4, s0
	s_addc_u32 s13, s5, s1
	s_lshl_b64 s[0:1], s[52:53], 1
	s_add_u32 s0, s2, s0
	s_addc_u32 s1, s3, s1
	v_lshl_add_u64 v[30:31], s[0:1], 0, v[112:113]
	s_mov_b32 s0, 2
	s_cmp_lt_u32 s22, 6
	v_cmp_gt_u32_e64 s[40:41], 32, v191
	v_add_u32_e32 v112, s14, v114
	v_lshl_add_u32 v198, v193, 2, s15
	v_lshl_add_u32 v1, v199, 2, s15
	s_waitcnt lgkmcnt(0)
	s_barrier
	s_cbranch_scc1 .LBB0_359
	v_add_u32_e32 v114, 0xc0, v112
	v_or_b32_e32 v170, 0xc0, v191
	s_mov_b32 s2, 5
	v_readfirstlane_b32 s100, v195
	v_mov_b32_e32 v218, v170
	v_ashrrev_i32_e32 v219, 31, v170
	v_lshlrev_b64 v[216:217], 11, v[218:219]
	v_lshlrev_b64 v[218:219], 9, v[218:219]
	v_lshl_add_u64 v[216:217], s[10:11], 0, v[216:217]
	v_lshl_add_u64 v[218:219], s[12:13], 0, v[218:219]
	s_add_i32 s0, s2, -1
	s_and_b32 s0, s0, 1
	s_mulk_i32 s0, 0x5100
	s_add_i32 s101, s100, s0
	s_branch .LBB0_350
.LBB0_349:
	v_pk_add_f32 v[66:67], v[66:67], v[200:201]
	v_pk_add_f32 v[68:69], v[68:69], v[6:7]
	v_pk_add_f32 v[70:71], v[70:71], v[8:9]
	v_pk_add_f32 v[72:73], v[72:73], v[10:11]
	v_pk_add_f32 v[74:75], v[74:75], v[12:13]
	v_pk_add_f32 v[76:77], v[76:77], v[14:15]
	v_pk_add_f32 v[78:79], v[78:79], v[16:17]
	v_add_f32_e32 v3, v64, v115
	v_add_f32_e32 v4, v65, v171
	v_pk_add_f32 v[66:67], v[66:67], v[68:69]
	v_pk_add_f32 v[70:71], v[70:71], v[72:73]
	v_pk_add_f32 v[74:75], v[74:75], v[76:77]
	v_add_f32_e32 v3, v3, v4
	v_pk_add_f32 v[66:67], v[66:67], v[70:71]
	v_pk_add_f32 v[74:75], v[74:75], v[78:79]
	v_pk_add_f32 v[66:67], v[66:67], v[74:75]
	v_add_f32_e32 v3, v3, v66
	v_add_f32_e32 v3, v3, v67
	s_add_i32 s2, s2, 1
	v_add_f32_e32 v163, v163, v3
	v_add_u32_e32 v114, 64, v114
	v_add_u32_e32 v170, 64, v170
	s_add_i32 s0, s2, -1
	s_and_b32 s0, s0, 1
	s_mulk_i32 s0, 0x5100
	s_add_i32 s101, s100, s0
	v_mov_b32_e32 v218, v170
	v_ashrrev_i32_e32 v219, 31, v170
	v_lshlrev_b64 v[216:217], 11, v[218:219]
	v_lshlrev_b64 v[218:219], 9, v[218:219]
	v_lshl_add_u64 v[216:217], s[10:11], 0, v[216:217]
	v_lshl_add_u64 v[218:219], s[12:13], 0, v[218:219]
	s_cmp_eq_u32 s22, s2
	s_waitcnt vmcnt(0)
	s_waitcnt lgkmcnt(0)
	s_barrier
	s_cbranch_scc1 .LBB0_358
.LBB0_350:
	s_add_i32 s0, s2, -1
	s_and_b32 s3, s0, 1
	s_xor_b32 s0, s3, 1
	s_mulk_i32 s0, 0x5100
	v_add_u32_e32 v84, s0, v197
	ds_read_b128 v[18:21], v84
	ds_read_b128 v[22:25], v84 offset:512
	s_mov_b32 m0, s101
	v_ashrrev_i32_e32 v115, 31, v114
	global_load_lds_dwordx4 v[216:217], off
	s_and_b64 vcc, exec, s[38:39]
	s_cbranch_vccnz .LBB0_352
	s_add_i32 m0, s101, 0x2000
	s_nop 0
	global_load_lds_dwordx4 v[218:219], off
.LBB0_352:
	s_waitcnt lgkmcnt(1)
	v_mfma_f32_32x32x16_bf16 v[2:17], v[18:21], v[116:119], v[96:111]
	s_waitcnt lgkmcnt(0)
	v_mfma_f32_32x32x16_bf16 v[64:79], v[22:25], v[116:119], v[96:111]
	ds_read_b128 v[18:21], v84 offset:2048
	ds_read_b128 v[22:25], v84 offset:2560
	s_waitcnt lgkmcnt(0)
	v_mfma_f32_32x32x16_bf16 v[64:79], v[22:25], v[120:123], v[64:79]
	v_mfma_f32_32x32x16_bf16 v[2:17], v[18:21], v[120:123], v[2:17]
	ds_read_b128 v[18:21], v84 offset:4096
	ds_read_b128 v[22:25], v84 offset:4608
	s_waitcnt lgkmcnt(0)
	v_mfma_f32_32x32x16_bf16 v[64:79], v[22:25], v[124:127], v[64:79]
	v_mfma_f32_32x32x16_bf16 v[2:17], v[18:21], v[124:127], v[2:17]
	ds_read_b128 v[18:21], v84 offset:6144
	ds_read_b128 v[22:25], v84 offset:6656
	s_waitcnt lgkmcnt(0)
	v_mfma_f32_32x32x16_bf16 v[64:79], v[22:25], v[128:131], v[64:79]
	v_lshlrev_b64 v[22:23], 11, v[114:115]
	s_add_i32 m0, s101, 0x2f80
	v_lshl_add_u64 v[26:27], v[30:31], 0, v[22:23]
	global_load_lds_dwordx4 v[26:27], off offset:128
	ds_read_b128 v[22:25], v84 offset:8704
	ds_read_b128 v[26:29], v84 offset:10240
	v_add_u32_e32 v115, s0, v196
	v_mfma_f32_32x32x16_bf16 v[2:17], v[18:21], v[128:131], v[2:17]
	ds_read_b128 v[18:21], v84 offset:8192
	s_waitcnt lgkmcnt(0)
	v_mfma_f32_32x32x16_bf16 v[2:17], v[18:21], v[132:135], v[2:17]
	ds_read_b64_tr_b16 v[152:153], v115 offset:12288
	ds_read_b64_tr_b16 v[154:155], v115 offset:12800
	ds_read_b64_tr_b16 v[88:89], v115 offset:13312
	ds_read_b64_tr_b16 v[90:91], v115 offset:13824
	ds_read_b64_tr_b16 v[80:81], v115 offset:14336
	ds_read_b64_tr_b16 v[82:83], v115 offset:14848
	ds_read_b64_tr_b16 v[18:19], v115 offset:15360
	ds_read_b64_tr_b16 v[20:21], v115 offset:15872
	ds_read_b128 v[200:203], v84 offset:10752
	v_mfma_f32_32x32x16_bf16 v[64:79], v[22:25], v[132:135], v[64:79]
	v_mfma_f32_32x32x16_bf16 v[2:17], v[26:29], v[136:139], v[2:17]
	ds_read_b64_tr_b16 v[92:93], v115 offset:16384
	ds_read_b64_tr_b16 v[94:95], v115 offset:16896
	ds_read_b64_tr_b16 v[84:85], v115 offset:17408
	ds_read_b64_tr_b16 v[86:87], v115 offset:17920
	ds_read_b64_tr_b16 v[26:27], v115 offset:18432
	ds_read_b64_tr_b16 v[28:29], v115 offset:18944
	ds_read_b64_tr_b16 v[22:23], v115 offset:19456
	ds_read_b64_tr_b16 v[24:25], v115 offset:19968
	s_waitcnt lgkmcnt(8)
	v_mfma_f32_32x32x16_bf16 v[64:79], v[200:203], v[136:139], v[64:79]
	v_max3_f32 v115, v2, v3, v64
	v_max3_f32 v171, v4, v5, v65
	v_max3_f32 v115, v115, v66, v67
	v_max3_f32 v171, v171, v8, v9
	v_max3_f32 v115, v115, v6, v7
	v_max3_f32 v171, v171, v70, v71
	v_max3_f32 v115, v115, v68, v69
	v_max3_f32 v171, v171, v12, v13
	v_max3_f32 v115, v115, v10, v11
	v_max3_f32 v171, v171, v74, v75
	v_max3_f32 v115, v115, v72, v73
	v_max3_f32 v171, v171, v16, v17
	v_max3_f32 v115, v115, v14, v15
	v_max3_f32 v171, v171, v78, v79
	v_max3_f32 v115, v115, v76, v77
	v_max_f32_e32 v115, v115, v171
	v_mov_b32_e32 v171, v115
	s_nop 1
	v_permlane32_swap_b32_e32 v115, v171
	v_max_f32_e32 v115, v115, v171
	v_cmp_lt_f32_e32 vcc, s75, v115
	s_cbranch_vccz .LBB0_356
	v_max_f32_e32 v96, v115, v115
	v_max_f32_e32 v98, 0, v96
	v_exp_f32_e64 v115, -v98
	s_and_saveexec_b64 s[0:1], s[40:41]
	ds_write_b32 v198, v115 offset:41472
	s_or_b64 exec, exec, s[0:1]
	s_waitcnt lgkmcnt(0)
	ds_read_b128 v[200:203], v1 offset:41472
	ds_read_b128 v[204:207], v1 offset:41504
	ds_read_b128 v[208:211], v1 offset:41536
	ds_read_b128 v[212:215], v1 offset:41568
	v_add_f32_e32 v0, v0, v98
	s_waitcnt lgkmcnt(0)
	v_xor_b32_e32 v96, 0x80000000, v0
	v_pk_add_f32 v[2:3], v[2:3], v[98:99] op_sel_hi:[1,0] neg_lo:[0,1] neg_hi:[0,1]
	v_pk_add_f32 v[64:65], v[64:65], v[98:99] op_sel_hi:[1,0] neg_lo:[0,1] neg_hi:[0,1]
	v_pk_add_f32 v[4:5], v[4:5], v[98:99] op_sel_hi:[1,0] neg_lo:[0,1] neg_hi:[0,1]
	v_pk_add_f32 v[66:67], v[66:67], v[98:99] op_sel_hi:[1,0] neg_lo:[0,1] neg_hi:[0,1]
	v_pk_add_f32 v[6:7], v[6:7], v[98:99] op_sel_hi:[1,0] neg_lo:[0,1] neg_hi:[0,1]
	v_pk_add_f32 v[68:69], v[68:69], v[98:99] op_sel_hi:[1,0] neg_lo:[0,1] neg_hi:[0,1]
	v_pk_add_f32 v[8:9], v[8:9], v[98:99] op_sel_hi:[1,0] neg_lo:[0,1] neg_hi:[0,1]
	v_pk_add_f32 v[70:71], v[70:71], v[98:99] op_sel_hi:[1,0] neg_lo:[0,1] neg_hi:[0,1]
	v_pk_add_f32 v[10:11], v[10:11], v[98:99] op_sel_hi:[1,0] neg_lo:[0,1] neg_hi:[0,1]
	v_pk_add_f32 v[72:73], v[72:73], v[98:99] op_sel_hi:[1,0] neg_lo:[0,1] neg_hi:[0,1]
	v_pk_add_f32 v[12:13], v[12:13], v[98:99] op_sel_hi:[1,0] neg_lo:[0,1] neg_hi:[0,1]
	v_pk_add_f32 v[74:75], v[74:75], v[98:99] op_sel_hi:[1,0] neg_lo:[0,1] neg_hi:[0,1]
	v_pk_add_f32 v[14:15], v[14:15], v[98:99] op_sel_hi:[1,0] neg_lo:[0,1] neg_hi:[0,1]
	v_pk_add_f32 v[76:77], v[76:77], v[98:99] op_sel_hi:[1,0] neg_lo:[0,1] neg_hi:[0,1]
	v_pk_add_f32 v[16:17], v[16:17], v[98:99] op_sel_hi:[1,0] neg_lo:[0,1] neg_hi:[0,1]
	v_pk_add_f32 v[78:79], v[78:79], v[98:99] op_sel_hi:[1,0] neg_lo:[0,1] neg_hi:[0,1]
	v_mov_b32_e32 v97, v96
	v_mov_b32_e32 v98, v96
	v_mov_b32_e32 v99, v96
	v_mov_b32_e32 v100, v96
	v_mov_b32_e32 v101, v96
	v_mov_b32_e32 v102, v96
	v_mov_b32_e32 v103, v96
	v_mov_b32_e32 v104, v96
	v_mov_b32_e32 v105, v96
	v_mov_b32_e32 v106, v96
	v_mov_b32_e32 v107, v96
	v_mov_b32_e32 v108, v96
	v_mov_b32_e32 v109, v96
	v_mov_b32_e32 v110, v96
	v_mov_b32_e32 v111, v96
	v_mul_f32_e32 v163, v163, v115
	s_waitcnt lgkmcnt(0)
	v_pk_mul_f32 v[46:47], v[46:47], v[214:215]
	v_pk_mul_f32 v[42:43], v[42:43], v[210:211]
	v_pk_mul_f32 v[38:39], v[38:39], v[206:207]
	v_pk_mul_f32 v[34:35], v[34:35], v[202:203]
	v_pk_mul_f32 v[44:45], v[44:45], v[212:213]
	v_pk_mul_f32 v[40:41], v[40:41], v[208:209]
	v_pk_mul_f32 v[36:37], v[36:37], v[204:205]
	v_pk_mul_f32 v[32:33], v[32:33], v[200:201]
	v_pk_mul_f32 v[62:63], v[62:63], v[214:215]
	v_pk_mul_f32 v[58:59], v[58:59], v[210:211]
	v_pk_mul_f32 v[54:55], v[54:55], v[206:207]
	v_pk_mul_f32 v[50:51], v[50:51], v[202:203]
	v_pk_mul_f32 v[60:61], v[60:61], v[212:213]
	v_pk_mul_f32 v[56:57], v[56:57], v[208:209]
	v_pk_mul_f32 v[52:53], v[52:53], v[204:205]
	v_pk_mul_f32 v[48:49], v[48:49], v[200:201]
